# rglru item bulk load: 9 loads in flight instead of serialized; prologue modulation GEMV: 32 loads in flight per batch
# speedup vs baseline: 1.0301x; 1.0193x over previous
.LBB0_172:
	s_mov_b32 s98, 0x3000
	s_mov_b32 s99, 0
	v_mov_b64_e32 v[56:57], v[4:5]
	global_load_dword v80, v[56:57], off
	v_lshl_add_u64 v[56:57], v[56:57], 0, s[98:99]
	global_load_dword v81, v[56:57], off
	v_lshl_add_u64 v[56:57], v[56:57], 0, s[98:99]
	global_load_dword v82, v[56:57], off
	v_lshl_add_u64 v[56:57], v[56:57], 0, s[98:99]
	global_load_dword v83, v[56:57], off
	v_lshl_add_u64 v[56:57], v[56:57], 0, s[98:99]
	global_load_dword v84, v[56:57], off
	v_lshl_add_u64 v[56:57], v[56:57], 0, s[98:99]
	global_load_dword v85, v[56:57], off
	v_lshl_add_u64 v[56:57], v[56:57], 0, s[98:99]
	global_load_dword v86, v[56:57], off
	v_lshl_add_u64 v[56:57], v[56:57], 0, s[98:99]
	global_load_dword v87, v[56:57], off
	v_lshl_add_u64 v[56:57], v[56:57], 0, s[98:99]
	global_load_dword v88, v[56:57], off
	v_lshl_add_u64 v[56:57], v[56:57], 0, s[98:99]
	global_load_dword v89, v[56:57], off
	v_lshl_add_u64 v[56:57], v[56:57], 0, s[98:99]
	global_load_dword v90, v[56:57], off
	v_lshl_add_u64 v[56:57], v[56:57], 0, s[98:99]
	global_load_dword v91, v[56:57], off
	v_lshl_add_u64 v[56:57], v[56:57], 0, s[98:99]
	global_load_dword v92, v[56:57], off
	v_lshl_add_u64 v[56:57], v[56:57], 0, s[98:99]
	global_load_dword v93, v[56:57], off
	v_lshl_add_u64 v[56:57], v[56:57], 0, s[98:99]
	global_load_dword v94, v[56:57], off
	v_lshl_add_u64 v[56:57], v[56:57], 0, s[98:99]
	global_load_dword v95, v[56:57], off
	v_lshl_add_u64 v[56:57], v[56:57], 0, s[98:99]
	global_load_dword v96, v[56:57], off
	v_lshl_add_u64 v[56:57], v[56:57], 0, s[98:99]
	global_load_dword v97, v[56:57], off
	v_lshl_add_u64 v[56:57], v[56:57], 0, s[98:99]
	global_load_dword v98, v[56:57], off
	v_lshl_add_u64 v[56:57], v[56:57], 0, s[98:99]
	global_load_dword v99, v[56:57], off
	v_lshl_add_u64 v[56:57], v[56:57], 0, s[98:99]
	global_load_dword v100, v[56:57], off
	v_lshl_add_u64 v[56:57], v[56:57], 0, s[98:99]
	global_load_dword v101, v[56:57], off
	v_lshl_add_u64 v[56:57], v[56:57], 0, s[98:99]
	global_load_dword v102, v[56:57], off
	v_lshl_add_u64 v[56:57], v[56:57], 0, s[98:99]
	global_load_dword v103, v[56:57], off
	v_lshl_add_u64 v[56:57], v[56:57], 0, s[98:99]
	global_load_dword v104, v[56:57], off
	v_lshl_add_u64 v[56:57], v[56:57], 0, s[98:99]
	global_load_dword v105, v[56:57], off
	v_lshl_add_u64 v[56:57], v[56:57], 0, s[98:99]
	global_load_dword v106, v[56:57], off
	v_lshl_add_u64 v[56:57], v[56:57], 0, s[98:99]
	global_load_dword v107, v[56:57], off
	v_lshl_add_u64 v[56:57], v[56:57], 0, s[98:99]
	global_load_dword v108, v[56:57], off
	v_lshl_add_u64 v[56:57], v[56:57], 0, s[98:99]
	global_load_dword v109, v[56:57], off
	v_lshl_add_u64 v[56:57], v[56:57], 0, s[98:99]
	global_load_dword v110, v[56:57], off
	v_lshl_add_u64 v[56:57], v[56:57], 0, s[98:99]
	global_load_dword v111, v[56:57], off
	v_lshl_add_u64 v[56:57], v[56:57], 0, s[98:99]
	ds_read_b128 v[16:19], v0
	ds_read_b128 v[20:23], v0 offset:16
	ds_read_b128 v[24:27], v0 offset:4096
	ds_read_b128 v[28:31], v0 offset:4112
	ds_read_b128 v[32:35], v0 offset:8192
	ds_read_b128 v[36:39], v0 offset:8208
	ds_read_b128 v[40:43], v0 offset:12288
	ds_read_b128 v[44:47], v0 offset:12304
	ds_read_b128 v[48:51], v0 offset:16384
	ds_read_b128 v[52:55], v0 offset:16400
	v_add_u32_e32 v0, 32, v0
	s_waitcnt lgkmcnt(0)
	s_waitcnt vmcnt(31)
	v_fmac_f32_e32 v14, v80, v16
	v_fmac_f32_e32 v9, v80, v24
	v_fmac_f32_e32 v8, v80, v32
	v_fmac_f32_e32 v7, v80, v40
	v_fmac_f32_e32 v6, v80, v48
	s_waitcnt vmcnt(30)
	v_fmac_f32_e32 v14, v81, v17
	v_fmac_f32_e32 v9, v81, v25
	v_fmac_f32_e32 v8, v81, v33
	v_fmac_f32_e32 v7, v81, v41
	v_fmac_f32_e32 v6, v81, v49
	s_waitcnt vmcnt(29)
	v_fmac_f32_e32 v14, v82, v18
	v_fmac_f32_e32 v9, v82, v26
	v_fmac_f32_e32 v8, v82, v34
	v_fmac_f32_e32 v7, v82, v42
	v_fmac_f32_e32 v6, v82, v50
	s_waitcnt vmcnt(28)
	v_fmac_f32_e32 v14, v83, v19
	v_fmac_f32_e32 v9, v83, v27
	v_fmac_f32_e32 v8, v83, v35
	v_fmac_f32_e32 v7, v83, v43
	v_fmac_f32_e32 v6, v83, v51
	s_waitcnt vmcnt(27)
	v_fmac_f32_e32 v14, v84, v20
	v_fmac_f32_e32 v9, v84, v28
	v_fmac_f32_e32 v8, v84, v36
	v_fmac_f32_e32 v7, v84, v44
	v_fmac_f32_e32 v6, v84, v52
	s_waitcnt vmcnt(26)
	v_fmac_f32_e32 v14, v85, v21
	v_fmac_f32_e32 v9, v85, v29
	v_fmac_f32_e32 v8, v85, v37
	v_fmac_f32_e32 v7, v85, v45
	v_fmac_f32_e32 v6, v85, v53
	s_waitcnt vmcnt(25)
	v_fmac_f32_e32 v14, v86, v22
	v_fmac_f32_e32 v9, v86, v30
	v_fmac_f32_e32 v8, v86, v38
	v_fmac_f32_e32 v7, v86, v46
	v_fmac_f32_e32 v6, v86, v54
	s_waitcnt vmcnt(24)
	v_fmac_f32_e32 v14, v87, v23
	v_fmac_f32_e32 v9, v87, v31
	v_fmac_f32_e32 v8, v87, v39
	v_fmac_f32_e32 v7, v87, v47
	v_fmac_f32_e32 v6, v87, v55
	ds_read_b128 v[16:19], v0
	ds_read_b128 v[20:23], v0 offset:16
	ds_read_b128 v[24:27], v0 offset:4096
	ds_read_b128 v[28:31], v0 offset:4112
	ds_read_b128 v[32:35], v0 offset:8192
	ds_read_b128 v[36:39], v0 offset:8208
	ds_read_b128 v[40:43], v0 offset:12288
	ds_read_b128 v[44:47], v0 offset:12304
	ds_read_b128 v[48:51], v0 offset:16384
	ds_read_b128 v[52:55], v0 offset:16400
	v_add_u32_e32 v0, 32, v0
	s_waitcnt lgkmcnt(0)
	s_waitcnt vmcnt(23)
	v_fmac_f32_e32 v14, v88, v16
	v_fmac_f32_e32 v9, v88, v24
	v_fmac_f32_e32 v8, v88, v32
	v_fmac_f32_e32 v7, v88, v40
	v_fmac_f32_e32 v6, v88, v48
	s_waitcnt vmcnt(22)
	v_fmac_f32_e32 v14, v89, v17
	v_fmac_f32_e32 v9, v89, v25
	v_fmac_f32_e32 v8, v89, v33
	v_fmac_f32_e32 v7, v89, v41
	v_fmac_f32_e32 v6, v89, v49
	s_waitcnt vmcnt(21)
	v_fmac_f32_e32 v14, v90, v18
	v_fmac_f32_e32 v9, v90, v26
	v_fmac_f32_e32 v8, v90, v34
	v_fmac_f32_e32 v7, v90, v42
	v_fmac_f32_e32 v6, v90, v50
	s_waitcnt vmcnt(20)
	v_fmac_f32_e32 v14, v91, v19
	v_fmac_f32_e32 v9, v91, v27
	v_fmac_f32_e32 v8, v91, v35
	v_fmac_f32_e32 v7, v91, v43
	v_fmac_f32_e32 v6, v91, v51
	s_waitcnt vmcnt(19)
	v_fmac_f32_e32 v14, v92, v20
	v_fmac_f32_e32 v9, v92, v28
	v_fmac_f32_e32 v8, v92, v36
	v_fmac_f32_e32 v7, v92, v44
	v_fmac_f32_e32 v6, v92, v52
	s_waitcnt vmcnt(18)
	v_fmac_f32_e32 v14, v93, v21
	v_fmac_f32_e32 v9, v93, v29
	v_fmac_f32_e32 v8, v93, v37
	v_fmac_f32_e32 v7, v93, v45
	v_fmac_f32_e32 v6, v93, v53
	s_waitcnt vmcnt(17)
	v_fmac_f32_e32 v14, v94, v22
	v_fmac_f32_e32 v9, v94, v30
	v_fmac_f32_e32 v8, v94, v38
	v_fmac_f32_e32 v7, v94, v46
	v_fmac_f32_e32 v6, v94, v54
	s_waitcnt vmcnt(16)
	v_fmac_f32_e32 v14, v95, v23
	v_fmac_f32_e32 v9, v95, v31
	v_fmac_f32_e32 v8, v95, v39
	v_fmac_f32_e32 v7, v95, v47
	v_fmac_f32_e32 v6, v95, v55
	ds_read_b128 v[16:19], v0
	ds_read_b128 v[20:23], v0 offset:16
	ds_read_b128 v[24:27], v0 offset:4096
	ds_read_b128 v[28:31], v0 offset:4112
	ds_read_b128 v[32:35], v0 offset:8192
	ds_read_b128 v[36:39], v0 offset:8208
	ds_read_b128 v[40:43], v0 offset:12288
	ds_read_b128 v[44:47], v0 offset:12304
	ds_read_b128 v[48:51], v0 offset:16384
	ds_read_b128 v[52:55], v0 offset:16400
	v_add_u32_e32 v0, 32, v0
	s_waitcnt lgkmcnt(0)
	s_waitcnt vmcnt(15)
	v_fmac_f32_e32 v14, v96, v16
	v_fmac_f32_e32 v9, v96, v24
	v_fmac_f32_e32 v8, v96, v32
	v_fmac_f32_e32 v7, v96, v40
	v_fmac_f32_e32 v6, v96, v48
	s_waitcnt vmcnt(14)
	v_fmac_f32_e32 v14, v97, v17
	v_fmac_f32_e32 v9, v97, v25
	v_fmac_f32_e32 v8, v97, v33
	v_fmac_f32_e32 v7, v97, v41
	v_fmac_f32_e32 v6, v97, v49
	s_waitcnt vmcnt(13)
	v_fmac_f32_e32 v14, v98, v18
	v_fmac_f32_e32 v9, v98, v26
	v_fmac_f32_e32 v8, v98, v34
	v_fmac_f32_e32 v7, v98, v42
	v_fmac_f32_e32 v6, v98, v50
	s_waitcnt vmcnt(12)
	v_fmac_f32_e32 v14, v99, v19
	v_fmac_f32_e32 v9, v99, v27
	v_fmac_f32_e32 v8, v99, v35
	v_fmac_f32_e32 v7, v99, v43
	v_fmac_f32_e32 v6, v99, v51
	s_waitcnt vmcnt(11)
	v_fmac_f32_e32 v14, v100, v20
	v_fmac_f32_e32 v9, v100, v28
	v_fmac_f32_e32 v8, v100, v36
	v_fmac_f32_e32 v7, v100, v44
	v_fmac_f32_e32 v6, v100, v52
	s_waitcnt vmcnt(10)
	v_fmac_f32_e32 v14, v101, v21
	v_fmac_f32_e32 v9, v101, v29
	v_fmac_f32_e32 v8, v101, v37
	v_fmac_f32_e32 v7, v101, v45
	v_fmac_f32_e32 v6, v101, v53
	s_waitcnt vmcnt(9)
	v_fmac_f32_e32 v14, v102, v22
	v_fmac_f32_e32 v9, v102, v30
	v_fmac_f32_e32 v8, v102, v38
	v_fmac_f32_e32 v7, v102, v46
	v_fmac_f32_e32 v6, v102, v54
	s_waitcnt vmcnt(8)
	v_fmac_f32_e32 v14, v103, v23
	v_fmac_f32_e32 v9, v103, v31
	v_fmac_f32_e32 v8, v103, v39
	v_fmac_f32_e32 v7, v103, v47
	v_fmac_f32_e32 v6, v103, v55
	ds_read_b128 v[16:19], v0
	ds_read_b128 v[20:23], v0 offset:16
	ds_read_b128 v[24:27], v0 offset:4096
	ds_read_b128 v[28:31], v0 offset:4112
	ds_read_b128 v[32:35], v0 offset:8192
	ds_read_b128 v[36:39], v0 offset:8208
	ds_read_b128 v[40:43], v0 offset:12288
	ds_read_b128 v[44:47], v0 offset:12304
	ds_read_b128 v[48:51], v0 offset:16384
	ds_read_b128 v[52:55], v0 offset:16400
	v_add_u32_e32 v0, 32, v0
	s_waitcnt lgkmcnt(0)
	s_waitcnt vmcnt(7)
	v_fmac_f32_e32 v14, v104, v16
	v_fmac_f32_e32 v9, v104, v24
	v_fmac_f32_e32 v8, v104, v32
	v_fmac_f32_e32 v7, v104, v40
	v_fmac_f32_e32 v6, v104, v48
	s_waitcnt vmcnt(6)
	v_fmac_f32_e32 v14, v105, v17
	v_fmac_f32_e32 v9, v105, v25
	v_fmac_f32_e32 v8, v105, v33
	v_fmac_f32_e32 v7, v105, v41
	v_fmac_f32_e32 v6, v105, v49
	s_waitcnt vmcnt(5)
	v_fmac_f32_e32 v14, v106, v18
	v_fmac_f32_e32 v9, v106, v26
	v_fmac_f32_e32 v8, v106, v34
	v_fmac_f32_e32 v7, v106, v42
	v_fmac_f32_e32 v6, v106, v50
	s_waitcnt vmcnt(4)
	v_fmac_f32_e32 v14, v107, v19
	v_fmac_f32_e32 v9, v107, v27
	v_fmac_f32_e32 v8, v107, v35
	v_fmac_f32_e32 v7, v107, v43
	v_fmac_f32_e32 v6, v107, v51
	s_waitcnt vmcnt(3)
	v_fmac_f32_e32 v14, v108, v20
	v_fmac_f32_e32 v9, v108, v28
	v_fmac_f32_e32 v8, v108, v36
	v_fmac_f32_e32 v7, v108, v44
	v_fmac_f32_e32 v6, v108, v52
	s_waitcnt vmcnt(2)
	v_fmac_f32_e32 v14, v109, v21
	v_fmac_f32_e32 v9, v109, v29
	v_fmac_f32_e32 v8, v109, v37
	v_fmac_f32_e32 v7, v109, v45
	v_fmac_f32_e32 v6, v109, v53
	s_waitcnt vmcnt(1)
	v_fmac_f32_e32 v14, v110, v22
	v_fmac_f32_e32 v9, v110, v30
	v_fmac_f32_e32 v8, v110, v38
	v_fmac_f32_e32 v7, v110, v46
	v_fmac_f32_e32 v6, v110, v54
	s_waitcnt vmcnt(0)
	v_fmac_f32_e32 v14, v111, v23
	v_fmac_f32_e32 v9, v111, v31
	v_fmac_f32_e32 v8, v111, v39
	v_fmac_f32_e32 v7, v111, v47
	v_fmac_f32_e32 v6, v111, v55
	global_load_dword v80, v[56:57], off
	v_lshl_add_u64 v[56:57], v[56:57], 0, s[98:99]
	global_load_dword v81, v[56:57], off
	v_lshl_add_u64 v[56:57], v[56:57], 0, s[98:99]
	global_load_dword v82, v[56:57], off
	v_lshl_add_u64 v[56:57], v[56:57], 0, s[98:99]
	global_load_dword v83, v[56:57], off
	v_lshl_add_u64 v[56:57], v[56:57], 0, s[98:99]
	global_load_dword v84, v[56:57], off
	v_lshl_add_u64 v[56:57], v[56:57], 0, s[98:99]
	global_load_dword v85, v[56:57], off
	v_lshl_add_u64 v[56:57], v[56:57], 0, s[98:99]
	global_load_dword v86, v[56:57], off
	v_lshl_add_u64 v[56:57], v[56:57], 0, s[98:99]
	global_load_dword v87, v[56:57], off
	v_lshl_add_u64 v[56:57], v[56:57], 0, s[98:99]
	global_load_dword v88, v[56:57], off
	v_lshl_add_u64 v[56:57], v[56:57], 0, s[98:99]
	global_load_dword v89, v[56:57], off
	v_lshl_add_u64 v[56:57], v[56:57], 0, s[98:99]
	global_load_dword v90, v[56:57], off
	v_lshl_add_u64 v[56:57], v[56:57], 0, s[98:99]
	global_load_dword v91, v[56:57], off
	v_lshl_add_u64 v[56:57], v[56:57], 0, s[98:99]
	global_load_dword v92, v[56:57], off
	v_lshl_add_u64 v[56:57], v[56:57], 0, s[98:99]
	global_load_dword v93, v[56:57], off
	v_lshl_add_u64 v[56:57], v[56:57], 0, s[98:99]
	global_load_dword v94, v[56:57], off
	v_lshl_add_u64 v[56:57], v[56:57], 0, s[98:99]
	global_load_dword v95, v[56:57], off
	v_lshl_add_u64 v[56:57], v[56:57], 0, s[98:99]
	global_load_dword v96, v[56:57], off
	v_lshl_add_u64 v[56:57], v[56:57], 0, s[98:99]
	global_load_dword v97, v[56:57], off
	v_lshl_add_u64 v[56:57], v[56:57], 0, s[98:99]
	global_load_dword v98, v[56:57], off
	v_lshl_add_u64 v[56:57], v[56:57], 0, s[98:99]
	global_load_dword v99, v[56:57], off
	v_lshl_add_u64 v[56:57], v[56:57], 0, s[98:99]
	global_load_dword v100, v[56:57], off
	v_lshl_add_u64 v[56:57], v[56:57], 0, s[98:99]
	global_load_dword v101, v[56:57], off
	v_lshl_add_u64 v[56:57], v[56:57], 0, s[98:99]
	global_load_dword v102, v[56:57], off
	v_lshl_add_u64 v[56:57], v[56:57], 0, s[98:99]
	global_load_dword v103, v[56:57], off
	v_lshl_add_u64 v[56:57], v[56:57], 0, s[98:99]
	global_load_dword v104, v[56:57], off
	v_lshl_add_u64 v[56:57], v[56:57], 0, s[98:99]
	global_load_dword v105, v[56:57], off
	v_lshl_add_u64 v[56:57], v[56:57], 0, s[98:99]
	global_load_dword v106, v[56:57], off
	v_lshl_add_u64 v[56:57], v[56:57], 0, s[98:99]
	global_load_dword v107, v[56:57], off
	v_lshl_add_u64 v[56:57], v[56:57], 0, s[98:99]
	global_load_dword v108, v[56:57], off
	v_lshl_add_u64 v[56:57], v[56:57], 0, s[98:99]
	global_load_dword v109, v[56:57], off
	v_lshl_add_u64 v[56:57], v[56:57], 0, s[98:99]
	global_load_dword v110, v[56:57], off
	v_lshl_add_u64 v[56:57], v[56:57], 0, s[98:99]
	global_load_dword v111, v[56:57], off
	v_lshl_add_u64 v[56:57], v[56:57], 0, s[98:99]
	ds_read_b128 v[16:19], v0
	ds_read_b128 v[20:23], v0 offset:16
	ds_read_b128 v[24:27], v0 offset:4096
	ds_read_b128 v[28:31], v0 offset:4112
	ds_read_b128 v[32:35], v0 offset:8192
	ds_read_b128 v[36:39], v0 offset:8208
	ds_read_b128 v[40:43], v0 offset:12288
	ds_read_b128 v[44:47], v0 offset:12304
	ds_read_b128 v[48:51], v0 offset:16384
	ds_read_b128 v[52:55], v0 offset:16400
	v_add_u32_e32 v0, 32, v0
	s_waitcnt lgkmcnt(0)
	s_waitcnt vmcnt(31)
	v_fmac_f32_e32 v14, v80, v16
	v_fmac_f32_e32 v9, v80, v24
	v_fmac_f32_e32 v8, v80, v32
	v_fmac_f32_e32 v7, v80, v40
	v_fmac_f32_e32 v6, v80, v48
	s_waitcnt vmcnt(30)
	v_fmac_f32_e32 v14, v81, v17
	v_fmac_f32_e32 v9, v81, v25
	v_fmac_f32_e32 v8, v81, v33
	v_fmac_f32_e32 v7, v81, v41
	v_fmac_f32_e32 v6, v81, v49
	s_waitcnt vmcnt(29)
	v_fmac_f32_e32 v14, v82, v18
	v_fmac_f32_e32 v9, v82, v26
	v_fmac_f32_e32 v8, v82, v34
	v_fmac_f32_e32 v7, v82, v42
	v_fmac_f32_e32 v6, v82, v50
	s_waitcnt vmcnt(28)
	v_fmac_f32_e32 v14, v83, v19
	v_fmac_f32_e32 v9, v83, v27
	v_fmac_f32_e32 v8, v83, v35
	v_fmac_f32_e32 v7, v83, v43
	v_fmac_f32_e32 v6, v83, v51
	s_waitcnt vmcnt(27)
	v_fmac_f32_e32 v14, v84, v20
	v_fmac_f32_e32 v9, v84, v28
	v_fmac_f32_e32 v8, v84, v36
	v_fmac_f32_e32 v7, v84, v44
	v_fmac_f32_e32 v6, v84, v52
	s_waitcnt vmcnt(26)
	v_fmac_f32_e32 v14, v85, v21
	v_fmac_f32_e32 v9, v85, v29
	v_fmac_f32_e32 v8, v85, v37
	v_fmac_f32_e32 v7, v85, v45
	v_fmac_f32_e32 v6, v85, v53
	s_waitcnt vmcnt(25)
	v_fmac_f32_e32 v14, v86, v22
	v_fmac_f32_e32 v9, v86, v30
	v_fmac_f32_e32 v8, v86, v38
	v_fmac_f32_e32 v7, v86, v46
	v_fmac_f32_e32 v6, v86, v54
	s_waitcnt vmcnt(24)
	v_fmac_f32_e32 v14, v87, v23
	v_fmac_f32_e32 v9, v87, v31
	v_fmac_f32_e32 v8, v87, v39
	v_fmac_f32_e32 v7, v87, v47
	v_fmac_f32_e32 v6, v87, v55
	ds_read_b128 v[16:19], v0
	ds_read_b128 v[20:23], v0 offset:16
	ds_read_b128 v[24:27], v0 offset:4096
	ds_read_b128 v[28:31], v0 offset:4112
	ds_read_b128 v[32:35], v0 offset:8192
	ds_read_b128 v[36:39], v0 offset:8208
	ds_read_b128 v[40:43], v0 offset:12288
	ds_read_b128 v[44:47], v0 offset:12304
	ds_read_b128 v[48:51], v0 offset:16384
	ds_read_b128 v[52:55], v0 offset:16400
	v_add_u32_e32 v0, 32, v0
	s_waitcnt lgkmcnt(0)
	s_waitcnt vmcnt(23)
	v_fmac_f32_e32 v14, v88, v16
	v_fmac_f32_e32 v9, v88, v24
	v_fmac_f32_e32 v8, v88, v32
	v_fmac_f32_e32 v7, v88, v40
	v_fmac_f32_e32 v6, v88, v48
	s_waitcnt vmcnt(22)
	v_fmac_f32_e32 v14, v89, v17
	v_fmac_f32_e32 v9, v89, v25
	v_fmac_f32_e32 v8, v89, v33
	v_fmac_f32_e32 v7, v89, v41
	v_fmac_f32_e32 v6, v89, v49
	s_waitcnt vmcnt(21)
	v_fmac_f32_e32 v14, v90, v18
	v_fmac_f32_e32 v9, v90, v26
	v_fmac_f32_e32 v8, v90, v34
	v_fmac_f32_e32 v7, v90, v42
	v_fmac_f32_e32 v6, v90, v50
	s_waitcnt vmcnt(20)
	v_fmac_f32_e32 v14, v91, v19
	v_fmac_f32_e32 v9, v91, v27
	v_fmac_f32_e32 v8, v91, v35
	v_fmac_f32_e32 v7, v91, v43
	v_fmac_f32_e32 v6, v91, v51
	s_waitcnt vmcnt(19)
	v_fmac_f32_e32 v14, v92, v20
	v_fmac_f32_e32 v9, v92, v28
	v_fmac_f32_e32 v8, v92, v36
	v_fmac_f32_e32 v7, v92, v44
	v_fmac_f32_e32 v6, v92, v52
	s_waitcnt vmcnt(18)
	v_fmac_f32_e32 v14, v93, v21
	v_fmac_f32_e32 v9, v93, v29
	v_fmac_f32_e32 v8, v93, v37
	v_fmac_f32_e32 v7, v93, v45
	v_fmac_f32_e32 v6, v93, v53
	s_waitcnt vmcnt(17)
	v_fmac_f32_e32 v14, v94, v22
	v_fmac_f32_e32 v9, v94, v30
	v_fmac_f32_e32 v8, v94, v38
	v_fmac_f32_e32 v7, v94, v46
	v_fmac_f32_e32 v6, v94, v54
	s_waitcnt vmcnt(16)
	v_fmac_f32_e32 v14, v95, v23
	v_fmac_f32_e32 v9, v95, v31
	v_fmac_f32_e32 v8, v95, v39
	v_fmac_f32_e32 v7, v95, v47
	v_fmac_f32_e32 v6, v95, v55
	ds_read_b128 v[16:19], v0
	ds_read_b128 v[20:23], v0 offset:16
	ds_read_b128 v[24:27], v0 offset:4096
	ds_read_b128 v[28:31], v0 offset:4112
	ds_read_b128 v[32:35], v0 offset:8192
	ds_read_b128 v[36:39], v0 offset:8208
	ds_read_b128 v[40:43], v0 offset:12288
	ds_read_b128 v[44:47], v0 offset:12304
	ds_read_b128 v[48:51], v0 offset:16384
	ds_read_b128 v[52:55], v0 offset:16400
	v_add_u32_e32 v0, 32, v0
	s_waitcnt lgkmcnt(0)
	s_waitcnt vmcnt(15)
	v_fmac_f32_e32 v14, v96, v16
	v_fmac_f32_e32 v9, v96, v24
	v_fmac_f32_e32 v8, v96, v32
	v_fmac_f32_e32 v7, v96, v40
	v_fmac_f32_e32 v6, v96, v48
	s_waitcnt vmcnt(14)
	v_fmac_f32_e32 v14, v97, v17
	v_fmac_f32_e32 v9, v97, v25
	v_fmac_f32_e32 v8, v97, v33
	v_fmac_f32_e32 v7, v97, v41
	v_fmac_f32_e32 v6, v97, v49
	s_waitcnt vmcnt(13)
	v_fmac_f32_e32 v14, v98, v18
	v_fmac_f32_e32 v9, v98, v26
	v_fmac_f32_e32 v8, v98, v34
	v_fmac_f32_e32 v7, v98, v42
	v_fmac_f32_e32 v6, v98, v50
	s_waitcnt vmcnt(12)
	v_fmac_f32_e32 v14, v99, v19
	v_fmac_f32_e32 v9, v99, v27
	v_fmac_f32_e32 v8, v99, v35
	v_fmac_f32_e32 v7, v99, v43
	v_fmac_f32_e32 v6, v99, v51
	s_waitcnt vmcnt(11)
	v_fmac_f32_e32 v14, v100, v20
	v_fmac_f32_e32 v9, v100, v28
	v_fmac_f32_e32 v8, v100, v36
	v_fmac_f32_e32 v7, v100, v44
	v_fmac_f32_e32 v6, v100, v52
	s_waitcnt vmcnt(10)
	v_fmac_f32_e32 v14, v101, v21
	v_fmac_f32_e32 v9, v101, v29
	v_fmac_f32_e32 v8, v101, v37
	v_fmac_f32_e32 v7, v101, v45
	v_fmac_f32_e32 v6, v101, v53
	s_waitcnt vmcnt(9)
	v_fmac_f32_e32 v14, v102, v22
	v_fmac_f32_e32 v9, v102, v30
	v_fmac_f32_e32 v8, v102, v38
	v_fmac_f32_e32 v7, v102, v46
	v_fmac_f32_e32 v6, v102, v54
	s_waitcnt vmcnt(8)
	v_fmac_f32_e32 v14, v103, v23
	v_fmac_f32_e32 v9, v103, v31
	v_fmac_f32_e32 v8, v103, v39
	v_fmac_f32_e32 v7, v103, v47
	v_fmac_f32_e32 v6, v103, v55
	ds_read_b128 v[16:19], v0
	ds_read_b128 v[20:23], v0 offset:16
	ds_read_b128 v[24:27], v0 offset:4096
	ds_read_b128 v[28:31], v0 offset:4112
	ds_read_b128 v[32:35], v0 offset:8192
	ds_read_b128 v[36:39], v0 offset:8208
	ds_read_b128 v[40:43], v0 offset:12288
	ds_read_b128 v[44:47], v0 offset:12304
	ds_read_b128 v[48:51], v0 offset:16384
	ds_read_b128 v[52:55], v0 offset:16400
	v_add_u32_e32 v0, 32, v0
	s_waitcnt lgkmcnt(0)
	s_waitcnt vmcnt(7)
	v_fmac_f32_e32 v14, v104, v16
	v_fmac_f32_e32 v9, v104, v24
	v_fmac_f32_e32 v8, v104, v32
	v_fmac_f32_e32 v7, v104, v40
	v_fmac_f32_e32 v6, v104, v48
	s_waitcnt vmcnt(6)
	v_fmac_f32_e32 v14, v105, v17
	v_fmac_f32_e32 v9, v105, v25
	v_fmac_f32_e32 v8, v105, v33
	v_fmac_f32_e32 v7, v105, v41
	v_fmac_f32_e32 v6, v105, v49
	s_waitcnt vmcnt(5)
	v_fmac_f32_e32 v14, v106, v18
	v_fmac_f32_e32 v9, v106, v26
	v_fmac_f32_e32 v8, v106, v34
	v_fmac_f32_e32 v7, v106, v42
	v_fmac_f32_e32 v6, v106, v50
	s_waitcnt vmcnt(4)
	v_fmac_f32_e32 v14, v107, v19
	v_fmac_f32_e32 v9, v107, v27
	v_fmac_f32_e32 v8, v107, v35
	v_fmac_f32_e32 v7, v107, v43
	v_fmac_f32_e32 v6, v107, v51
	s_waitcnt vmcnt(3)
	v_fmac_f32_e32 v14, v108, v20
	v_fmac_f32_e32 v9, v108, v28
	v_fmac_f32_e32 v8, v108, v36
	v_fmac_f32_e32 v7, v108, v44
	v_fmac_f32_e32 v6, v108, v52
	s_waitcnt vmcnt(2)
	v_fmac_f32_e32 v14, v109, v21
	v_fmac_f32_e32 v9, v109, v29
	v_fmac_f32_e32 v8, v109, v37
	v_fmac_f32_e32 v7, v109, v45
	v_fmac_f32_e32 v6, v109, v53
	s_waitcnt vmcnt(1)
	v_fmac_f32_e32 v14, v110, v22
	v_fmac_f32_e32 v9, v110, v30
	v_fmac_f32_e32 v8, v110, v38
	v_fmac_f32_e32 v7, v110, v46
	v_fmac_f32_e32 v6, v110, v54
	s_waitcnt vmcnt(0)
	v_fmac_f32_e32 v14, v111, v23
	v_fmac_f32_e32 v9, v111, v31
	v_fmac_f32_e32 v8, v111, v39
	v_fmac_f32_e32 v7, v111, v47
	v_fmac_f32_e32 v6, v111, v55
	global_load_dword v80, v[56:57], off
	v_lshl_add_u64 v[56:57], v[56:57], 0, s[98:99]
	global_load_dword v81, v[56:57], off
	v_lshl_add_u64 v[56:57], v[56:57], 0, s[98:99]
	global_load_dword v82, v[56:57], off
	v_lshl_add_u64 v[56:57], v[56:57], 0, s[98:99]
	global_load_dword v83, v[56:57], off
	v_lshl_add_u64 v[56:57], v[56:57], 0, s[98:99]
	global_load_dword v84, v[56:57], off
	v_lshl_add_u64 v[56:57], v[56:57], 0, s[98:99]
	global_load_dword v85, v[56:57], off
	v_lshl_add_u64 v[56:57], v[56:57], 0, s[98:99]
	global_load_dword v86, v[56:57], off
	v_lshl_add_u64 v[56:57], v[56:57], 0, s[98:99]
	global_load_dword v87, v[56:57], off
	v_lshl_add_u64 v[56:57], v[56:57], 0, s[98:99]
	global_load_dword v88, v[56:57], off
	v_lshl_add_u64 v[56:57], v[56:57], 0, s[98:99]
	global_load_dword v89, v[56:57], off
	v_lshl_add_u64 v[56:57], v[56:57], 0, s[98:99]
	global_load_dword v90, v[56:57], off
	v_lshl_add_u64 v[56:57], v[56:57], 0, s[98:99]
	global_load_dword v91, v[56:57], off
	v_lshl_add_u64 v[56:57], v[56:57], 0, s[98:99]
	global_load_dword v92, v[56:57], off
	v_lshl_add_u64 v[56:57], v[56:57], 0, s[98:99]
	global_load_dword v93, v[56:57], off
	v_lshl_add_u64 v[56:57], v[56:57], 0, s[98:99]
	global_load_dword v94, v[56:57], off
	v_lshl_add_u64 v[56:57], v[56:57], 0, s[98:99]
	global_load_dword v95, v[56:57], off
	v_lshl_add_u64 v[56:57], v[56:57], 0, s[98:99]
	global_load_dword v96, v[56:57], off
	v_lshl_add_u64 v[56:57], v[56:57], 0, s[98:99]
	global_load_dword v97, v[56:57], off
	v_lshl_add_u64 v[56:57], v[56:57], 0, s[98:99]
	global_load_dword v98, v[56:57], off
	v_lshl_add_u64 v[56:57], v[56:57], 0, s[98:99]
	global_load_dword v99, v[56:57], off
	v_lshl_add_u64 v[56:57], v[56:57], 0, s[98:99]
	global_load_dword v100, v[56:57], off
	v_lshl_add_u64 v[56:57], v[56:57], 0, s[98:99]
	global_load_dword v101, v[56:57], off
	v_lshl_add_u64 v[56:57], v[56:57], 0, s[98:99]
	global_load_dword v102, v[56:57], off
	v_lshl_add_u64 v[56:57], v[56:57], 0, s[98:99]
	global_load_dword v103, v[56:57], off
	v_lshl_add_u64 v[56:57], v[56:57], 0, s[98:99]
	global_load_dword v104, v[56:57], off
	v_lshl_add_u64 v[56:57], v[56:57], 0, s[98:99]
	global_load_dword v105, v[56:57], off
	v_lshl_add_u64 v[56:57], v[56:57], 0, s[98:99]
	global_load_dword v106, v[56:57], off
	v_lshl_add_u64 v[56:57], v[56:57], 0, s[98:99]
	global_load_dword v107, v[56:57], off
	v_lshl_add_u64 v[56:57], v[56:57], 0, s[98:99]
	global_load_dword v108, v[56:57], off
	v_lshl_add_u64 v[56:57], v[56:57], 0, s[98:99]
	global_load_dword v109, v[56:57], off
	v_lshl_add_u64 v[56:57], v[56:57], 0, s[98:99]
	global_load_dword v110, v[56:57], off
	v_lshl_add_u64 v[56:57], v[56:57], 0, s[98:99]
	global_load_dword v111, v[56:57], off
	v_lshl_add_u64 v[56:57], v[56:57], 0, s[98:99]
	ds_read_b128 v[16:19], v0
	ds_read_b128 v[20:23], v0 offset:16
	ds_read_b128 v[24:27], v0 offset:4096
	ds_read_b128 v[28:31], v0 offset:4112
	ds_read_b128 v[32:35], v0 offset:8192
	ds_read_b128 v[36:39], v0 offset:8208
	ds_read_b128 v[40:43], v0 offset:12288
	ds_read_b128 v[44:47], v0 offset:12304
	ds_read_b128 v[48:51], v0 offset:16384
	ds_read_b128 v[52:55], v0 offset:16400
	v_add_u32_e32 v0, 32, v0
	s_waitcnt lgkmcnt(0)
	s_waitcnt vmcnt(31)
	v_fmac_f32_e32 v14, v80, v16
	v_fmac_f32_e32 v9, v80, v24
	v_fmac_f32_e32 v8, v80, v32
	v_fmac_f32_e32 v7, v80, v40
	v_fmac_f32_e32 v6, v80, v48
	s_waitcnt vmcnt(30)
	v_fmac_f32_e32 v14, v81, v17
	v_fmac_f32_e32 v9, v81, v25
	v_fmac_f32_e32 v8, v81, v33
	v_fmac_f32_e32 v7, v81, v41
	v_fmac_f32_e32 v6, v81, v49
	s_waitcnt vmcnt(29)
	v_fmac_f32_e32 v14, v82, v18
	v_fmac_f32_e32 v9, v82, v26
	v_fmac_f32_e32 v8, v82, v34
	v_fmac_f32_e32 v7, v82, v42
	v_fmac_f32_e32 v6, v82, v50
	s_waitcnt vmcnt(28)
	v_fmac_f32_e32 v14, v83, v19
	v_fmac_f32_e32 v9, v83, v27
	v_fmac_f32_e32 v8, v83, v35
	v_fmac_f32_e32 v7, v83, v43
	v_fmac_f32_e32 v6, v83, v51
	s_waitcnt vmcnt(27)
	v_fmac_f32_e32 v14, v84, v20
	v_fmac_f32_e32 v9, v84, v28
	v_fmac_f32_e32 v8, v84, v36
	v_fmac_f32_e32 v7, v84, v44
	v_fmac_f32_e32 v6, v84, v52
	s_waitcnt vmcnt(26)
	v_fmac_f32_e32 v14, v85, v21
	v_fmac_f32_e32 v9, v85, v29
	v_fmac_f32_e32 v8, v85, v37
	v_fmac_f32_e32 v7, v85, v45
	v_fmac_f32_e32 v6, v85, v53
	s_waitcnt vmcnt(25)
	v_fmac_f32_e32 v14, v86, v22
	v_fmac_f32_e32 v9, v86, v30
	v_fmac_f32_e32 v8, v86, v38
	v_fmac_f32_e32 v7, v86, v46
	v_fmac_f32_e32 v6, v86, v54
	s_waitcnt vmcnt(24)
	v_fmac_f32_e32 v14, v87, v23
	v_fmac_f32_e32 v9, v87, v31
	v_fmac_f32_e32 v8, v87, v39
	v_fmac_f32_e32 v7, v87, v47
	v_fmac_f32_e32 v6, v87, v55
	ds_read_b128 v[16:19], v0
	ds_read_b128 v[20:23], v0 offset:16
	ds_read_b128 v[24:27], v0 offset:4096
	ds_read_b128 v[28:31], v0 offset:4112
	ds_read_b128 v[32:35], v0 offset:8192
	ds_read_b128 v[36:39], v0 offset:8208
	ds_read_b128 v[40:43], v0 offset:12288
	ds_read_b128 v[44:47], v0 offset:12304
	ds_read_b128 v[48:51], v0 offset:16384
	ds_read_b128 v[52:55], v0 offset:16400
	v_add_u32_e32 v0, 32, v0
	s_waitcnt lgkmcnt(0)
	s_waitcnt vmcnt(23)
	v_fmac_f32_e32 v14, v88, v16
	v_fmac_f32_e32 v9, v88, v24
	v_fmac_f32_e32 v8, v88, v32
	v_fmac_f32_e32 v7, v88, v40
	v_fmac_f32_e32 v6, v88, v48
	s_waitcnt vmcnt(22)
	v_fmac_f32_e32 v14, v89, v17
	v_fmac_f32_e32 v9, v89, v25
	v_fmac_f32_e32 v8, v89, v33
	v_fmac_f32_e32 v7, v89, v41
	v_fmac_f32_e32 v6, v89, v49
	s_waitcnt vmcnt(21)
	v_fmac_f32_e32 v14, v90, v18
	v_fmac_f32_e32 v9, v90, v26
	v_fmac_f32_e32 v8, v90, v34
	v_fmac_f32_e32 v7, v90, v42
	v_fmac_f32_e32 v6, v90, v50
	s_waitcnt vmcnt(20)
	v_fmac_f32_e32 v14, v91, v19
	v_fmac_f32_e32 v9, v91, v27
	v_fmac_f32_e32 v8, v91, v35
	v_fmac_f32_e32 v7, v91, v43
	v_fmac_f32_e32 v6, v91, v51
	s_waitcnt vmcnt(19)
	v_fmac_f32_e32 v14, v92, v20
	v_fmac_f32_e32 v9, v92, v28
	v_fmac_f32_e32 v8, v92, v36
	v_fmac_f32_e32 v7, v92, v44
	v_fmac_f32_e32 v6, v92, v52
	s_waitcnt vmcnt(18)
	v_fmac_f32_e32 v14, v93, v21
	v_fmac_f32_e32 v9, v93, v29
	v_fmac_f32_e32 v8, v93, v37
	v_fmac_f32_e32 v7, v93, v45
	v_fmac_f32_e32 v6, v93, v53
	s_waitcnt vmcnt(17)
	v_fmac_f32_e32 v14, v94, v22
	v_fmac_f32_e32 v9, v94, v30
	v_fmac_f32_e32 v8, v94, v38
	v_fmac_f32_e32 v7, v94, v46
	v_fmac_f32_e32 v6, v94, v54
	s_waitcnt vmcnt(16)
	v_fmac_f32_e32 v14, v95, v23
	v_fmac_f32_e32 v9, v95, v31
	v_fmac_f32_e32 v8, v95, v39
	v_fmac_f32_e32 v7, v95, v47
	v_fmac_f32_e32 v6, v95, v55
	ds_read_b128 v[16:19], v0
	ds_read_b128 v[20:23], v0 offset:16
	ds_read_b128 v[24:27], v0 offset:4096
	ds_read_b128 v[28:31], v0 offset:4112
	ds_read_b128 v[32:35], v0 offset:8192
	ds_read_b128 v[36:39], v0 offset:8208
	ds_read_b128 v[40:43], v0 offset:12288
	ds_read_b128 v[44:47], v0 offset:12304
	ds_read_b128 v[48:51], v0 offset:16384
	ds_read_b128 v[52:55], v0 offset:16400
	v_add_u32_e32 v0, 32, v0
	s_waitcnt lgkmcnt(0)
	s_waitcnt vmcnt(15)
	v_fmac_f32_e32 v14, v96, v16
	v_fmac_f32_e32 v9, v96, v24
	v_fmac_f32_e32 v8, v96, v32
	v_fmac_f32_e32 v7, v96, v40
	v_fmac_f32_e32 v6, v96, v48
	s_waitcnt vmcnt(14)
	v_fmac_f32_e32 v14, v97, v17
	v_fmac_f32_e32 v9, v97, v25
	v_fmac_f32_e32 v8, v97, v33
	v_fmac_f32_e32 v7, v97, v41
	v_fmac_f32_e32 v6, v97, v49
	s_waitcnt vmcnt(13)
	v_fmac_f32_e32 v14, v98, v18
	v_fmac_f32_e32 v9, v98, v26
	v_fmac_f32_e32 v8, v98, v34
	v_fmac_f32_e32 v7, v98, v42
	v_fmac_f32_e32 v6, v98, v50
	s_waitcnt vmcnt(12)
	v_fmac_f32_e32 v14, v99, v19
	v_fmac_f32_e32 v9, v99, v27
	v_fmac_f32_e32 v8, v99, v35
	v_fmac_f32_e32 v7, v99, v43
	v_fmac_f32_e32 v6, v99, v51
	s_waitcnt vmcnt(11)
	v_fmac_f32_e32 v14, v100, v20
	v_fmac_f32_e32 v9, v100, v28
	v_fmac_f32_e32 v8, v100, v36
	v_fmac_f32_e32 v7, v100, v44
	v_fmac_f32_e32 v6, v100, v52
	s_waitcnt vmcnt(10)
	v_fmac_f32_e32 v14, v101, v21
	v_fmac_f32_e32 v9, v101, v29
	v_fmac_f32_e32 v8, v101, v37
	v_fmac_f32_e32 v7, v101, v45
	v_fmac_f32_e32 v6, v101, v53
	s_waitcnt vmcnt(9)
	v_fmac_f32_e32 v14, v102, v22
	v_fmac_f32_e32 v9, v102, v30
	v_fmac_f32_e32 v8, v102, v38
	v_fmac_f32_e32 v7, v102, v46
	v_fmac_f32_e32 v6, v102, v54
	s_waitcnt vmcnt(8)
	v_fmac_f32_e32 v14, v103, v23
	v_fmac_f32_e32 v9, v103, v31
	v_fmac_f32_e32 v8, v103, v39
	v_fmac_f32_e32 v7, v103, v47
	v_fmac_f32_e32 v6, v103, v55
	ds_read_b128 v[16:19], v0
	ds_read_b128 v[20:23], v0 offset:16
	ds_read_b128 v[24:27], v0 offset:4096
	ds_read_b128 v[28:31], v0 offset:4112
	ds_read_b128 v[32:35], v0 offset:8192
	ds_read_b128 v[36:39], v0 offset:8208
	ds_read_b128 v[40:43], v0 offset:12288
	ds_read_b128 v[44:47], v0 offset:12304
	ds_read_b128 v[48:51], v0 offset:16384
	ds_read_b128 v[52:55], v0 offset:16400
	v_add_u32_e32 v0, 32, v0
	s_waitcnt lgkmcnt(0)
	s_waitcnt vmcnt(7)
	v_fmac_f32_e32 v14, v104, v16
	v_fmac_f32_e32 v9, v104, v24
	v_fmac_f32_e32 v8, v104, v32
	v_fmac_f32_e32 v7, v104, v40
	v_fmac_f32_e32 v6, v104, v48
	s_waitcnt vmcnt(6)
	v_fmac_f32_e32 v14, v105, v17
	v_fmac_f32_e32 v9, v105, v25
	v_fmac_f32_e32 v8, v105, v33
	v_fmac_f32_e32 v7, v105, v41
	v_fmac_f32_e32 v6, v105, v49
	s_waitcnt vmcnt(5)
	v_fmac_f32_e32 v14, v106, v18
	v_fmac_f32_e32 v9, v106, v26
	v_fmac_f32_e32 v8, v106, v34
	v_fmac_f32_e32 v7, v106, v42
	v_fmac_f32_e32 v6, v106, v50
	s_waitcnt vmcnt(4)
	v_fmac_f32_e32 v14, v107, v19
	v_fmac_f32_e32 v9, v107, v27
	v_fmac_f32_e32 v8, v107, v35
	v_fmac_f32_e32 v7, v107, v43
	v_fmac_f32_e32 v6, v107, v51
	s_waitcnt vmcnt(3)
	v_fmac_f32_e32 v14, v108, v20
	v_fmac_f32_e32 v9, v108, v28
	v_fmac_f32_e32 v8, v108, v36
	v_fmac_f32_e32 v7, v108, v44
	v_fmac_f32_e32 v6, v108, v52
	s_waitcnt vmcnt(2)
	v_fmac_f32_e32 v14, v109, v21
	v_fmac_f32_e32 v9, v109, v29
	v_fmac_f32_e32 v8, v109, v37
	v_fmac_f32_e32 v7, v109, v45
	v_fmac_f32_e32 v6, v109, v53
	s_waitcnt vmcnt(1)
	v_fmac_f32_e32 v14, v110, v22
	v_fmac_f32_e32 v9, v110, v30
	v_fmac_f32_e32 v8, v110, v38
	v_fmac_f32_e32 v7, v110, v46
	v_fmac_f32_e32 v6, v110, v54
	s_waitcnt vmcnt(0)
	v_fmac_f32_e32 v14, v111, v23
	v_fmac_f32_e32 v9, v111, v31
	v_fmac_f32_e32 v8, v111, v39
	v_fmac_f32_e32 v7, v111, v47
	v_fmac_f32_e32 v6, v111, v55
	global_load_dword v80, v[56:57], off
	v_lshl_add_u64 v[56:57], v[56:57], 0, s[98:99]
	global_load_dword v81, v[56:57], off
	v_lshl_add_u64 v[56:57], v[56:57], 0, s[98:99]
	global_load_dword v82, v[56:57], off
	v_lshl_add_u64 v[56:57], v[56:57], 0, s[98:99]
	global_load_dword v83, v[56:57], off
	v_lshl_add_u64 v[56:57], v[56:57], 0, s[98:99]
	global_load_dword v84, v[56:57], off
	v_lshl_add_u64 v[56:57], v[56:57], 0, s[98:99]
	global_load_dword v85, v[56:57], off
	v_lshl_add_u64 v[56:57], v[56:57], 0, s[98:99]
	global_load_dword v86, v[56:57], off
	v_lshl_add_u64 v[56:57], v[56:57], 0, s[98:99]
	global_load_dword v87, v[56:57], off
	v_lshl_add_u64 v[56:57], v[56:57], 0, s[98:99]
	global_load_dword v88, v[56:57], off
	v_lshl_add_u64 v[56:57], v[56:57], 0, s[98:99]
	global_load_dword v89, v[56:57], off
	v_lshl_add_u64 v[56:57], v[56:57], 0, s[98:99]
	global_load_dword v90, v[56:57], off
	v_lshl_add_u64 v[56:57], v[56:57], 0, s[98:99]
	global_load_dword v91, v[56:57], off
	v_lshl_add_u64 v[56:57], v[56:57], 0, s[98:99]
	global_load_dword v92, v[56:57], off
	v_lshl_add_u64 v[56:57], v[56:57], 0, s[98:99]
	global_load_dword v93, v[56:57], off
	v_lshl_add_u64 v[56:57], v[56:57], 0, s[98:99]
	global_load_dword v94, v[56:57], off
	v_lshl_add_u64 v[56:57], v[56:57], 0, s[98:99]
	global_load_dword v95, v[56:57], off
	v_lshl_add_u64 v[56:57], v[56:57], 0, s[98:99]
	global_load_dword v96, v[56:57], off
	v_lshl_add_u64 v[56:57], v[56:57], 0, s[98:99]
	global_load_dword v97, v[56:57], off
	v_lshl_add_u64 v[56:57], v[56:57], 0, s[98:99]
	global_load_dword v98, v[56:57], off
	v_lshl_add_u64 v[56:57], v[56:57], 0, s[98:99]
	global_load_dword v99, v[56:57], off
	v_lshl_add_u64 v[56:57], v[56:57], 0, s[98:99]
	global_load_dword v100, v[56:57], off
	v_lshl_add_u64 v[56:57], v[56:57], 0, s[98:99]
	global_load_dword v101, v[56:57], off
	v_lshl_add_u64 v[56:57], v[56:57], 0, s[98:99]
	global_load_dword v102, v[56:57], off
	v_lshl_add_u64 v[56:57], v[56:57], 0, s[98:99]
	global_load_dword v103, v[56:57], off
	v_lshl_add_u64 v[56:57], v[56:57], 0, s[98:99]
	global_load_dword v104, v[56:57], off
	v_lshl_add_u64 v[56:57], v[56:57], 0, s[98:99]
	global_load_dword v105, v[56:57], off
	v_lshl_add_u64 v[56:57], v[56:57], 0, s[98:99]
	global_load_dword v106, v[56:57], off
	v_lshl_add_u64 v[56:57], v[56:57], 0, s[98:99]
	global_load_dword v107, v[56:57], off
	v_lshl_add_u64 v[56:57], v[56:57], 0, s[98:99]
	global_load_dword v108, v[56:57], off
	v_lshl_add_u64 v[56:57], v[56:57], 0, s[98:99]
	global_load_dword v109, v[56:57], off
	v_lshl_add_u64 v[56:57], v[56:57], 0, s[98:99]
	global_load_dword v110, v[56:57], off
	v_lshl_add_u64 v[56:57], v[56:57], 0, s[98:99]
	global_load_dword v111, v[56:57], off
	v_lshl_add_u64 v[56:57], v[56:57], 0, s[98:99]
	ds_read_b128 v[16:19], v0
	ds_read_b128 v[20:23], v0 offset:16
	ds_read_b128 v[24:27], v0 offset:4096
	ds_read_b128 v[28:31], v0 offset:4112
	ds_read_b128 v[32:35], v0 offset:8192
	ds_read_b128 v[36:39], v0 offset:8208
	ds_read_b128 v[40:43], v0 offset:12288
	ds_read_b128 v[44:47], v0 offset:12304
	ds_read_b128 v[48:51], v0 offset:16384
	ds_read_b128 v[52:55], v0 offset:16400
	v_add_u32_e32 v0, 32, v0
	s_waitcnt lgkmcnt(0)
	s_waitcnt vmcnt(31)
	v_fmac_f32_e32 v14, v80, v16
	v_fmac_f32_e32 v9, v80, v24
	v_fmac_f32_e32 v8, v80, v32
	v_fmac_f32_e32 v7, v80, v40
	v_fmac_f32_e32 v6, v80, v48
	s_waitcnt vmcnt(30)
	v_fmac_f32_e32 v14, v81, v17
	v_fmac_f32_e32 v9, v81, v25
	v_fmac_f32_e32 v8, v81, v33
	v_fmac_f32_e32 v7, v81, v41
	v_fmac_f32_e32 v6, v81, v49
	s_waitcnt vmcnt(29)
	v_fmac_f32_e32 v14, v82, v18
	v_fmac_f32_e32 v9, v82, v26
	v_fmac_f32_e32 v8, v82, v34
	v_fmac_f32_e32 v7, v82, v42
	v_fmac_f32_e32 v6, v82, v50
	s_waitcnt vmcnt(28)
	v_fmac_f32_e32 v14, v83, v19
	v_fmac_f32_e32 v9, v83, v27
	v_fmac_f32_e32 v8, v83, v35
	v_fmac_f32_e32 v7, v83, v43
	v_fmac_f32_e32 v6, v83, v51
	s_waitcnt vmcnt(27)
	v_fmac_f32_e32 v14, v84, v20
	v_fmac_f32_e32 v9, v84, v28
	v_fmac_f32_e32 v8, v84, v36
	v_fmac_f32_e32 v7, v84, v44
	v_fmac_f32_e32 v6, v84, v52
	s_waitcnt vmcnt(26)
	v_fmac_f32_e32 v14, v85, v21
	v_fmac_f32_e32 v9, v85, v29
	v_fmac_f32_e32 v8, v85, v37
	v_fmac_f32_e32 v7, v85, v45
	v_fmac_f32_e32 v6, v85, v53
	s_waitcnt vmcnt(25)
	v_fmac_f32_e32 v14, v86, v22
	v_fmac_f32_e32 v9, v86, v30
	v_fmac_f32_e32 v8, v86, v38
	v_fmac_f32_e32 v7, v86, v46
	v_fmac_f32_e32 v6, v86, v54
	s_waitcnt vmcnt(24)
	v_fmac_f32_e32 v14, v87, v23
	v_fmac_f32_e32 v9, v87, v31
	v_fmac_f32_e32 v8, v87, v39
	v_fmac_f32_e32 v7, v87, v47
	v_fmac_f32_e32 v6, v87, v55
	ds_read_b128 v[16:19], v0
	ds_read_b128 v[20:23], v0 offset:16
	ds_read_b128 v[24:27], v0 offset:4096
	ds_read_b128 v[28:31], v0 offset:4112
	ds_read_b128 v[32:35], v0 offset:8192
	ds_read_b128 v[36:39], v0 offset:8208
	ds_read_b128 v[40:43], v0 offset:12288
	ds_read_b128 v[44:47], v0 offset:12304
	ds_read_b128 v[48:51], v0 offset:16384
	ds_read_b128 v[52:55], v0 offset:16400
	v_add_u32_e32 v0, 32, v0
	s_waitcnt lgkmcnt(0)
	s_waitcnt vmcnt(23)
	v_fmac_f32_e32 v14, v88, v16
	v_fmac_f32_e32 v9, v88, v24
	v_fmac_f32_e32 v8, v88, v32
	v_fmac_f32_e32 v7, v88, v40
	v_fmac_f32_e32 v6, v88, v48
	s_waitcnt vmcnt(22)
	v_fmac_f32_e32 v14, v89, v17
	v_fmac_f32_e32 v9, v89, v25
	v_fmac_f32_e32 v8, v89, v33
	v_fmac_f32_e32 v7, v89, v41
	v_fmac_f32_e32 v6, v89, v49
	s_waitcnt vmcnt(21)
	v_fmac_f32_e32 v14, v90, v18
	v_fmac_f32_e32 v9, v90, v26
	v_fmac_f32_e32 v8, v90, v34
	v_fmac_f32_e32 v7, v90, v42
	v_fmac_f32_e32 v6, v90, v50
	s_waitcnt vmcnt(20)
	v_fmac_f32_e32 v14, v91, v19
	v_fmac_f32_e32 v9, v91, v27
	v_fmac_f32_e32 v8, v91, v35
	v_fmac_f32_e32 v7, v91, v43
	v_fmac_f32_e32 v6, v91, v51
	s_waitcnt vmcnt(19)
	v_fmac_f32_e32 v14, v92, v20
	v_fmac_f32_e32 v9, v92, v28
	v_fmac_f32_e32 v8, v92, v36
	v_fmac_f32_e32 v7, v92, v44
	v_fmac_f32_e32 v6, v92, v52
	s_waitcnt vmcnt(18)
	v_fmac_f32_e32 v14, v93, v21
	v_fmac_f32_e32 v9, v93, v29
	v_fmac_f32_e32 v8, v93, v37
	v_fmac_f32_e32 v7, v93, v45
	v_fmac_f32_e32 v6, v93, v53
	s_waitcnt vmcnt(17)
	v_fmac_f32_e32 v14, v94, v22
	v_fmac_f32_e32 v9, v94, v30
	v_fmac_f32_e32 v8, v94, v38
	v_fmac_f32_e32 v7, v94, v46
	v_fmac_f32_e32 v6, v94, v54
	s_waitcnt vmcnt(16)
	v_fmac_f32_e32 v14, v95, v23
	v_fmac_f32_e32 v9, v95, v31
	v_fmac_f32_e32 v8, v95, v39
	v_fmac_f32_e32 v7, v95, v47
	v_fmac_f32_e32 v6, v95, v55
	ds_read_b128 v[16:19], v0
	ds_read_b128 v[20:23], v0 offset:16
	ds_read_b128 v[24:27], v0 offset:4096
	ds_read_b128 v[28:31], v0 offset:4112
	ds_read_b128 v[32:35], v0 offset:8192
	ds_read_b128 v[36:39], v0 offset:8208
	ds_read_b128 v[40:43], v0 offset:12288
	ds_read_b128 v[44:47], v0 offset:12304
	ds_read_b128 v[48:51], v0 offset:16384
	ds_read_b128 v[52:55], v0 offset:16400
	v_add_u32_e32 v0, 32, v0
	s_waitcnt lgkmcnt(0)
	s_waitcnt vmcnt(15)
	v_fmac_f32_e32 v14, v96, v16
	v_fmac_f32_e32 v9, v96, v24
	v_fmac_f32_e32 v8, v96, v32
	v_fmac_f32_e32 v7, v96, v40
	v_fmac_f32_e32 v6, v96, v48
	s_waitcnt vmcnt(14)
	v_fmac_f32_e32 v14, v97, v17
	v_fmac_f32_e32 v9, v97, v25
	v_fmac_f32_e32 v8, v97, v33
	v_fmac_f32_e32 v7, v97, v41
	v_fmac_f32_e32 v6, v97, v49
	s_waitcnt vmcnt(13)
	v_fmac_f32_e32 v14, v98, v18
	v_fmac_f32_e32 v9, v98, v26
	v_fmac_f32_e32 v8, v98, v34
	v_fmac_f32_e32 v7, v98, v42
	v_fmac_f32_e32 v6, v98, v50
	s_waitcnt vmcnt(12)
	v_fmac_f32_e32 v14, v99, v19
	v_fmac_f32_e32 v9, v99, v27
	v_fmac_f32_e32 v8, v99, v35
	v_fmac_f32_e32 v7, v99, v43
	v_fmac_f32_e32 v6, v99, v51
	s_waitcnt vmcnt(11)
	v_fmac_f32_e32 v14, v100, v20
	v_fmac_f32_e32 v9, v100, v28
	v_fmac_f32_e32 v8, v100, v36
	v_fmac_f32_e32 v7, v100, v44
	v_fmac_f32_e32 v6, v100, v52
	s_waitcnt vmcnt(10)
	v_fmac_f32_e32 v14, v101, v21
	v_fmac_f32_e32 v9, v101, v29
	v_fmac_f32_e32 v8, v101, v37
	v_fmac_f32_e32 v7, v101, v45
	v_fmac_f32_e32 v6, v101, v53
	s_waitcnt vmcnt(9)
	v_fmac_f32_e32 v14, v102, v22
	v_fmac_f32_e32 v9, v102, v30
	v_fmac_f32_e32 v8, v102, v38
	v_fmac_f32_e32 v7, v102, v46
	v_fmac_f32_e32 v6, v102, v54
	s_waitcnt vmcnt(8)
	v_fmac_f32_e32 v14, v103, v23
	v_fmac_f32_e32 v9, v103, v31
	v_fmac_f32_e32 v8, v103, v39
	v_fmac_f32_e32 v7, v103, v47
	v_fmac_f32_e32 v6, v103, v55
	ds_read_b128 v[16:19], v0
	ds_read_b128 v[20:23], v0 offset:16
	ds_read_b128 v[24:27], v0 offset:4096
	ds_read_b128 v[28:31], v0 offset:4112
	ds_read_b128 v[32:35], v0 offset:8192
	ds_read_b128 v[36:39], v0 offset:8208
	ds_read_b128 v[40:43], v0 offset:12288
	ds_read_b128 v[44:47], v0 offset:12304
	ds_read_b128 v[48:51], v0 offset:16384
	ds_read_b128 v[52:55], v0 offset:16400
	v_add_u32_e32 v0, 32, v0
	s_waitcnt lgkmcnt(0)
	s_waitcnt vmcnt(7)
	v_fmac_f32_e32 v14, v104, v16
	v_fmac_f32_e32 v9, v104, v24
	v_fmac_f32_e32 v8, v104, v32
	v_fmac_f32_e32 v7, v104, v40
	v_fmac_f32_e32 v6, v104, v48
	s_waitcnt vmcnt(6)
	v_fmac_f32_e32 v14, v105, v17
	v_fmac_f32_e32 v9, v105, v25
	v_fmac_f32_e32 v8, v105, v33
	v_fmac_f32_e32 v7, v105, v41
	v_fmac_f32_e32 v6, v105, v49
	s_waitcnt vmcnt(5)
	v_fmac_f32_e32 v14, v106, v18
	v_fmac_f32_e32 v9, v106, v26
	v_fmac_f32_e32 v8, v106, v34
	v_fmac_f32_e32 v7, v106, v42
	v_fmac_f32_e32 v6, v106, v50
	s_waitcnt vmcnt(4)
	v_fmac_f32_e32 v14, v107, v19
	v_fmac_f32_e32 v9, v107, v27
	v_fmac_f32_e32 v8, v107, v35
	v_fmac_f32_e32 v7, v107, v43
	v_fmac_f32_e32 v6, v107, v51
	s_waitcnt vmcnt(3)
	v_fmac_f32_e32 v14, v108, v20
	v_fmac_f32_e32 v9, v108, v28
	v_fmac_f32_e32 v8, v108, v36
	v_fmac_f32_e32 v7, v108, v44
	v_fmac_f32_e32 v6, v108, v52
	s_waitcnt vmcnt(2)
	v_fmac_f32_e32 v14, v109, v21
	v_fmac_f32_e32 v9, v109, v29
	v_fmac_f32_e32 v8, v109, v37
	v_fmac_f32_e32 v7, v109, v45
	v_fmac_f32_e32 v6, v109, v53
	s_waitcnt vmcnt(1)
	v_fmac_f32_e32 v14, v110, v22
	v_fmac_f32_e32 v9, v110, v30
	v_fmac_f32_e32 v8, v110, v38
	v_fmac_f32_e32 v7, v110, v46
	v_fmac_f32_e32 v6, v110, v54
	s_waitcnt vmcnt(0)
	v_fmac_f32_e32 v14, v111, v23
	v_fmac_f32_e32 v9, v111, v31
	v_fmac_f32_e32 v8, v111, v39
	v_fmac_f32_e32 v7, v111, v47
	v_fmac_f32_e32 v6, v111, v55
	ds_write_b32 v10, v14 offset:20480
	ds_write2st64_b32 v11, v9, v8 offset0:81 offset1:82
	ds_write2st64_b32 v11, v7, v6 offset0:83 offset1:84
	s_waitcnt lgkmcnt(0)
	s_barrier
	s_and_saveexec_b64 s[0:1], vcc
	s_cbranch_execz .LBB0_170
	s_mul_i32 s10, s20, 0xc00
	s_add_i32 s10, s10, s4
	v_or_b32_e32 v4, s10, v66
	v_ashrrev_i32_e32 v5, 31, v4
	v_lshl_add_u64 v[4:5], v[4:5], 2, s[8:9]
	global_load_dword v20, v[4:5], off
	ds_read2st64_b32 v[4:5], v13 offset0:80 offset1:85
	ds_read2st64_b32 v[6:7], v13 offset0:90 offset1:95
	ds_read2st64_b32 v[8:9], v13 offset0:100 offset1:105
	ds_read2st64_b32 v[14:15], v13 offset0:110 offset1:115
	v_mad_i64_i32 v[16:17], s[10:11], s20, 5, v[64:65]
	v_mov_b64_e32 v[18:19], s[2:3]
	v_mad_u64_u32 v[18:19], s[10:11], v16, s12, v[18:19]
	v_mad_i32_i24 v19, v17, s12, v19
	v_lshlrev_b32_e32 v0, 2, v66
	v_lshl_add_u64 v[16:17], s[4:5], 2, v[18:19]
	s_waitcnt vmcnt(0) lgkmcnt(3)
	v_add_f32_e32 v4, v20, v4
	v_add_f32_e32 v4, v4, v5
	s_waitcnt lgkmcnt(2)
	v_add_f32_e32 v4, v4, v6
	v_add_f32_e32 v4, v4, v7
	s_waitcnt lgkmcnt(1)
	v_add_f32_e32 v4, v4, v8
	v_add_f32_e32 v4, v4, v9
	s_waitcnt lgkmcnt(0)
	v_add_f32_e32 v4, v4, v14
	v_add_f32_e32 v6, v4, v15
	v_lshl_add_u64 v[4:5], v[16:17], 0, v[0:1]
	global_store_dword v[4:5], v6, off
	s_branch .LBB0_170

.LBB0_1507:
	s_lshl_b32 s14, s56, 7
	s_ashr_i32 s15, s14, 31
	s_lshl_b64 s[0:1], s[14:15], 1
	v_add_u32_e32 v70, s6, v156
	v_mov_b64_e32 v[64:65], s[0:1]
	v_mad_i64_i32 v[64:65], s[0:1], v70, s53, v[64:65]
	v_lshl_add_u64 v[68:69], v[120:121], 0, v[64:65]
	s_mov_b64 s[6:7], 0
	v_mov_b32_e32 v71, v155
	v_mov_b32_e32 v72, v153
	s_waitcnt vmcnt(0)
	s_barrier
	v_mov_b64_e32 v[212:213], 0
	v_mov_b64_e32 v[214:215], 0
	v_cmp_le_i32_e32 vcc, s9, v70
	v_cmp_gt_i32_e64 s[0:1], s10, v70
	s_and_b64 s[12:13], vcc, s[0:1]
	s_and_saveexec_b64 s[0:1], s[12:13]
	s_cbranch_execz .Lrgl_p1_0
	global_load_dwordx4 v[212:215], v[68:69], off
.Lrgl_p1_0:
	s_or_b64 exec, exec, s[0:1]
	v_lshl_add_u64 v[68:69], v[68:69], 0, s[38:39]
	v_mov_b64_e32 v[216:217], 0
	v_mov_b64_e32 v[218:219], 0
	v_add_u32_e32 v70, 32, v70
	v_cmp_le_i32_e32 vcc, s9, v70
	v_cmp_gt_i32_e64 s[0:1], s10, v70
	s_and_b64 s[12:13], vcc, s[0:1]
	s_and_saveexec_b64 s[0:1], s[12:13]
	s_cbranch_execz .Lrgl_p1_1
	global_load_dwordx4 v[216:219], v[68:69], off
.Lrgl_p1_1:
	s_or_b64 exec, exec, s[0:1]
	v_lshl_add_u64 v[68:69], v[68:69], 0, s[38:39]
	v_mov_b64_e32 v[220:221], 0
	v_mov_b64_e32 v[222:223], 0
	v_add_u32_e32 v70, 32, v70
	v_cmp_le_i32_e32 vcc, s9, v70
	v_cmp_gt_i32_e64 s[0:1], s10, v70
	s_and_b64 s[12:13], vcc, s[0:1]
	s_and_saveexec_b64 s[0:1], s[12:13]
	s_cbranch_execz .Lrgl_p1_2
	global_load_dwordx4 v[220:223], v[68:69], off
.Lrgl_p1_2:
	s_or_b64 exec, exec, s[0:1]
	v_lshl_add_u64 v[68:69], v[68:69], 0, s[38:39]
	v_mov_b64_e32 v[224:225], 0
	v_mov_b64_e32 v[226:227], 0
	v_add_u32_e32 v70, 32, v70
	v_cmp_le_i32_e32 vcc, s9, v70
	v_cmp_gt_i32_e64 s[0:1], s10, v70
	s_and_b64 s[12:13], vcc, s[0:1]
	s_and_saveexec_b64 s[0:1], s[12:13]
	s_cbranch_execz .Lrgl_p1_3
	global_load_dwordx4 v[224:227], v[68:69], off
.Lrgl_p1_3:
	s_or_b64 exec, exec, s[0:1]
	v_lshl_add_u64 v[68:69], v[68:69], 0, s[38:39]
	v_mov_b64_e32 v[228:229], 0
	v_mov_b64_e32 v[230:231], 0
	v_add_u32_e32 v70, 32, v70
	v_cmp_le_i32_e32 vcc, s9, v70
	v_cmp_gt_i32_e64 s[0:1], s10, v70
	s_and_b64 s[12:13], vcc, s[0:1]
	s_and_saveexec_b64 s[0:1], s[12:13]
	s_cbranch_execz .Lrgl_p1_4
	global_load_dwordx4 v[228:231], v[68:69], off
.Lrgl_p1_4:
	s_or_b64 exec, exec, s[0:1]
	v_lshl_add_u64 v[68:69], v[68:69], 0, s[38:39]
	v_mov_b64_e32 v[232:233], 0
	v_mov_b64_e32 v[234:235], 0
	v_add_u32_e32 v70, 32, v70
	v_cmp_le_i32_e32 vcc, s9, v70
	v_cmp_gt_i32_e64 s[0:1], s10, v70
	s_and_b64 s[12:13], vcc, s[0:1]
	s_and_saveexec_b64 s[0:1], s[12:13]
	s_cbranch_execz .Lrgl_p1_5
	global_load_dwordx4 v[232:235], v[68:69], off
.Lrgl_p1_5:
	s_or_b64 exec, exec, s[0:1]
	v_lshl_add_u64 v[68:69], v[68:69], 0, s[38:39]
	v_mov_b64_e32 v[236:237], 0
	v_mov_b64_e32 v[238:239], 0
	v_add_u32_e32 v70, 32, v70
	v_cmp_le_i32_e32 vcc, s9, v70
	v_cmp_gt_i32_e64 s[0:1], s10, v70
	s_and_b64 s[12:13], vcc, s[0:1]
	s_and_saveexec_b64 s[0:1], s[12:13]
	s_cbranch_execz .Lrgl_p1_6
	global_load_dwordx4 v[236:239], v[68:69], off
.Lrgl_p1_6:
	s_or_b64 exec, exec, s[0:1]
	v_lshl_add_u64 v[68:69], v[68:69], 0, s[38:39]
	v_mov_b64_e32 v[244:245], 0
	v_mov_b64_e32 v[246:247], 0
	v_add_u32_e32 v70, 32, v70
	v_cmp_le_i32_e32 vcc, s9, v70
	v_cmp_gt_i32_e64 s[0:1], s10, v70
	s_and_b64 s[12:13], vcc, s[0:1]
	s_and_saveexec_b64 s[0:1], s[12:13]
	s_cbranch_execz .Lrgl_p1_7
	global_load_dwordx4 v[244:247], v[68:69], off
.Lrgl_p1_7:
	s_or_b64 exec, exec, s[0:1]
	v_lshl_add_u64 v[68:69], v[68:69], 0, s[38:39]
	v_mov_b64_e32 v[248:249], 0
	v_mov_b64_e32 v[250:251], 0
	v_add_u32_e32 v70, 32, v70
	v_cmp_le_i32_e32 vcc, s9, v70
	v_cmp_gt_i32_e64 s[0:1], s10, v70
	s_and_b64 s[12:13], vcc, s[0:1]
	v_cmp_gt_u32_e64 s[0:1], 48, v154
	s_and_b64 s[12:13], s[12:13], s[0:1]
	s_and_saveexec_b64 s[0:1], s[12:13]
	s_cbranch_execz .Lrgl_p1_8
	global_load_dwordx4 v[248:251], v[68:69], off
.Lrgl_p1_8:
	s_or_b64 exec, exec, s[0:1]
	s_waitcnt vmcnt(0)
	ds_write_b128 v71, v[212:215]
	ds_write_b128 v71, v[216:219] offset:8704
	ds_write_b128 v71, v[220:223] offset:17408
	ds_write_b128 v71, v[224:227] offset:26112
	ds_write_b128 v71, v[228:231] offset:34816
	ds_write_b128 v71, v[232:235] offset:43520
	ds_write_b128 v71, v[236:239] offset:52224
	ds_write_b128 v71, v[244:247] offset:60928
	v_add_u32_e32 v71, 0x11000, v71
	v_cmp_gt_u32_e32 vcc, 48, v154
	s_and_saveexec_b64 s[0:1], vcc
	ds_write_b128 v71, v[248:251]
	s_or_b64 exec, exec, s[0:1]
.LBB0_1511:
	v_add_u32_e32 v124, s14, v117
	s_cmp_eq_u32 s56, s8
	v_ashrrev_i32_e32 v125, 31, v124
	s_cbranch_scc1 .LBB0_1518
	s_ashr_i32 s57, s56, 31
	s_lshl_b64 s[0:1], s[56:57], 15
	v_lshl_add_u64 v[48:49], v[118:119], 0, s[0:1]
	v_add_co_u32_e32 v20, vcc, 0xa0000, v48
	v_lshlrev_b64 v[56:57], 2, v[124:125]
	v_lshl_add_u64 v[28:29], v[48:49], 0, s[40:41]
	v_addc_co_u32_e32 v21, vcc, 0, v49, vcc
	v_lshl_add_u64 v[32:33], s[28:29], 0, v[56:57]
	global_load_dwordx4 v[0:3], v[48:49], off
	global_load_dwordx4 v[4:7], v[48:49], off offset:64
	global_load_dwordx4 v[8:11], v[48:49], off offset:128
	global_load_dwordx4 v[12:15], v[48:49], off offset:192
	global_load_dwordx4 v[16:19], v[28:29], off offset:64
	global_load_dwordx4 v[24:27], v[28:29], off offset:128
	s_nop 0
	global_load_dwordx4 v[20:23], v[20:21], off
	s_nop 0
	global_load_dwordx4 v[28:31], v[28:29], off offset:192
	v_lshl_add_u64 v[44:45], v[48:49], 0, s[42:43]
	global_load_dword v76, v[32:33], off
	v_add_co_u32_e32 v32, vcc, s69, v32
	v_lshl_add_u64 v[60:61], v[48:49], 0, s[44:45]
	s_nop 0
	v_addc_co_u32_e32 v33, vcc, 0, v33, vcc
	global_load_dword v77, v[32:33], off offset:1024
	v_add_co_u32_e32 v36, vcc, 0x50000, v48
	v_lshl_add_u64 v[62:63], s[24:25], 0, v[56:57]
	s_nop 0
	v_addc_co_u32_e32 v37, vcc, 0, v49, vcc
	v_add_co_u32_e32 v58, vcc, 0xf0000, v48
	global_load_dwordx4 v[32:35], v[44:45], off offset:64
	global_load_dwordx4 v[40:43], v[44:45], off offset:128
	s_nop 0
	global_load_dwordx4 v[36:39], v[36:37], off
	s_nop 0
	global_load_dwordx4 v[44:47], v[44:45], off offset:192
	v_addc_co_u32_e32 v59, vcc, 0, v49, vcc
	global_load_dwordx4 v[48:51], v[60:61], off offset:64
	global_load_dwordx4 v[52:55], v[60:61], off offset:128
	global_load_dword v67, v[62:63], off
	v_add_co_u32_e32 v62, vcc, s69, v62
	v_lshl_add_u64 v[56:57], s[26:27], 0, v[56:57]
	s_nop 0
	v_addc_co_u32_e32 v63, vcc, 0, v63, vcc
	global_load_dword v65, v[56:57], off
	v_add_co_u32_e32 v56, vcc, s69, v56
	global_load_dword v66, v[62:63], off offset:1024
	s_nop 0
	v_addc_co_u32_e32 v57, vcc, 0, v57, vcc
	global_load_dword v64, v[56:57], off offset:1024
	s_nop 0
	global_load_dwordx4 v[56:59], v[58:59], off
	s_nop 0
	global_load_dwordx4 v[60:63], v[60:61], off offset:192
	s_waitcnt vmcnt(13)
	v_mul_f32_e64 v68, |v76|, s16
	v_fma_f32 v69, |v76|, s16, -v68
	v_rndne_f32_e32 v70, v68
	v_fma_f32 v69, |v76|, s65, v69
	v_sub_f32_e32 v68, v68, v70
	v_add_f32_e32 v68, v68, v69
	s_waitcnt vmcnt(12)
	v_mul_f32_e64 v71, |v77|, s16
	v_fma_f32 v72, |v77|, s16, -v71
	v_rndne_f32_e32 v73, v71
	v_cvt_i32_f32_e32 v70, v70
	v_fma_f32 v69, |v77|, s65, v72
	v_sub_f32_e32 v71, v71, v73
	v_exp_f32_e32 v68, v68
	v_add_f32_e32 v69, v71, v69
	v_cvt_i32_f32_e32 v72, v73
	v_exp_f32_e32 v69, v69
	v_ldexp_f32 v68, v68, v70
	v_cmp_ngt_f32_e64 vcc, |v76|, s66
	v_ldexp_f32 v69, v69, v72
	s_nop 0
	v_cndmask_b32_e32 v68, 0, v68, vcc
	v_cmp_nlt_f32_e64 vcc, |v76|, s67
	s_nop 1
	v_cndmask_b32_e32 v74, v161, v68, vcc
	v_cmp_ngt_f32_e64 vcc, |v77|, s66
	v_add_f32_e32 v78, 1.0, v74
	v_cmp_lt_f32_e64 s[10:11], |v74|, s71
	v_cndmask_b32_e32 v68, 0, v69, vcc
	v_cmp_nlt_f32_e64 vcc, |v77|, s67
	s_nop 1
	v_cndmask_b32_e32 v75, v161, v68, vcc
	v_add_f32_e32 v79, 1.0, v75
	v_frexp_mant_f32_e32 v68, v78
	v_frexp_mant_f32_e32 v69, v79
	v_cmp_neq_f32_e32 vcc, s68, v74
	v_cmp_neq_f32_e64 s[8:9], s68, v75
	v_cmp_lt_f32_e64 s[6:7], |v75|, s71
	v_cmp_gt_f32_e64 s[0:1], s70, v68
	v_cmp_gt_f32_e64 s[12:13], s70, v69
	s_and_saveexec_b64 s[58:59], s[2:3]
	s_cbranch_execz .LBB0_1517
	v_or_b32_e32 v68, s14, v152
	v_ashrrev_i32_e32 v69, 31, v68
	v_lshl_add_u64 v[70:71], v[68:69], 2, s[22:23]
	s_mov_b64 s[60:61], 0
	v_mov_b32_e32 v69, v158
	v_mov_b32_e32 v80, v157
	v_mov_b32_e32 v81, v154
	s_branch .LBB0_1515

.LBB0_1661:
	s_lshl_b32 s76, s62, 7
	s_ashr_i32 s77, s76, 31
	s_lshl_b64 s[70:71], s[76:77], 1
	v_add_u32_e32 v70, s68, v189
	v_mov_b64_e32 v[64:65], s[70:71]
	v_mad_i64_i32 v[64:65], s[0:1], v70, s53, v[64:65]
	v_lshl_add_u64 v[68:69], v[168:169], 0, v[64:65]
	s_mov_b64 s[12:13], 0
	v_mov_b32_e32 v71, v188
	v_mov_b32_e32 v72, v159
	s_waitcnt vmcnt(0)
	s_barrier
	v_mov_b64_e32 v[220:221], 0
	v_mov_b64_e32 v[222:223], 0
	v_cmp_le_i32_e32 vcc, s15, v70
	v_cmp_gt_i32_e64 s[0:1], s16, v70
	s_and_b64 s[18:19], vcc, s[0:1]
	s_and_saveexec_b64 s[0:1], s[18:19]
	s_cbranch_execz .Lrgl_p2_0
	global_load_dwordx4 v[220:223], v[68:69], off
.Lrgl_p2_0:
	s_or_b64 exec, exec, s[0:1]
	v_lshl_add_u64 v[68:69], v[68:69], 0, s[44:45]
	v_mov_b64_e32 v[224:225], 0
	v_mov_b64_e32 v[226:227], 0
	v_add_u32_e32 v70, 32, v70
	v_cmp_le_i32_e32 vcc, s15, v70
	v_cmp_gt_i32_e64 s[0:1], s16, v70
	s_and_b64 s[18:19], vcc, s[0:1]
	s_and_saveexec_b64 s[0:1], s[18:19]
	s_cbranch_execz .Lrgl_p2_1
	global_load_dwordx4 v[224:227], v[68:69], off
.Lrgl_p2_1:
	s_or_b64 exec, exec, s[0:1]
	v_lshl_add_u64 v[68:69], v[68:69], 0, s[44:45]
	v_mov_b64_e32 v[228:229], 0
	v_mov_b64_e32 v[230:231], 0
	v_add_u32_e32 v70, 32, v70
	v_cmp_le_i32_e32 vcc, s15, v70
	v_cmp_gt_i32_e64 s[0:1], s16, v70
	s_and_b64 s[18:19], vcc, s[0:1]
	s_and_saveexec_b64 s[0:1], s[18:19]
	s_cbranch_execz .Lrgl_p2_2
	global_load_dwordx4 v[228:231], v[68:69], off
.Lrgl_p2_2:
	s_or_b64 exec, exec, s[0:1]
	v_lshl_add_u64 v[68:69], v[68:69], 0, s[44:45]
	v_mov_b64_e32 v[232:233], 0
	v_mov_b64_e32 v[234:235], 0
	v_add_u32_e32 v70, 32, v70
	v_cmp_le_i32_e32 vcc, s15, v70
	v_cmp_gt_i32_e64 s[0:1], s16, v70
	s_and_b64 s[18:19], vcc, s[0:1]
	s_and_saveexec_b64 s[0:1], s[18:19]
	s_cbranch_execz .Lrgl_p2_3
	global_load_dwordx4 v[232:235], v[68:69], off
.Lrgl_p2_3:
	s_or_b64 exec, exec, s[0:1]
	v_lshl_add_u64 v[68:69], v[68:69], 0, s[44:45]
	v_mov_b64_e32 v[236:237], 0
	v_mov_b64_e32 v[238:239], 0
	v_add_u32_e32 v70, 32, v70
	v_cmp_le_i32_e32 vcc, s15, v70
	v_cmp_gt_i32_e64 s[0:1], s16, v70
	s_and_b64 s[18:19], vcc, s[0:1]
	s_and_saveexec_b64 s[0:1], s[18:19]
	s_cbranch_execz .Lrgl_p2_4
	global_load_dwordx4 v[236:239], v[68:69], off
.Lrgl_p2_4:
	s_or_b64 exec, exec, s[0:1]
	v_lshl_add_u64 v[68:69], v[68:69], 0, s[44:45]
	v_mov_b64_e32 v[244:245], 0
	v_mov_b64_e32 v[246:247], 0
	v_add_u32_e32 v70, 32, v70
	v_cmp_le_i32_e32 vcc, s15, v70
	v_cmp_gt_i32_e64 s[0:1], s16, v70
	s_and_b64 s[18:19], vcc, s[0:1]
	s_and_saveexec_b64 s[0:1], s[18:19]
	s_cbranch_execz .Lrgl_p2_5
	global_load_dwordx4 v[244:247], v[68:69], off
.Lrgl_p2_5:
	s_or_b64 exec, exec, s[0:1]
	v_lshl_add_u64 v[68:69], v[68:69], 0, s[44:45]
	v_mov_b64_e32 v[248:249], 0
	v_mov_b64_e32 v[250:251], 0
	v_add_u32_e32 v70, 32, v70
	v_cmp_le_i32_e32 vcc, s15, v70
	v_cmp_gt_i32_e64 s[0:1], s16, v70
	s_and_b64 s[18:19], vcc, s[0:1]
	s_and_saveexec_b64 s[0:1], s[18:19]
	s_cbranch_execz .Lrgl_p2_6
	global_load_dwordx4 v[248:251], v[68:69], off
.Lrgl_p2_6:
	s_or_b64 exec, exec, s[0:1]
	v_lshl_add_u64 v[68:69], v[68:69], 0, s[44:45]
	v_mov_b64_e32 v[252:253], 0
	v_mov_b64_e32 v[254:255], 0
	v_add_u32_e32 v70, 32, v70
	v_cmp_le_i32_e32 vcc, s15, v70
	v_cmp_gt_i32_e64 s[0:1], s16, v70
	s_and_b64 s[18:19], vcc, s[0:1]
	s_and_saveexec_b64 s[0:1], s[18:19]
	s_cbranch_execz .Lrgl_p2_7
	global_load_dwordx4 v[252:255], v[68:69], off
.Lrgl_p2_7:
	s_or_b64 exec, exec, s[0:1]
	v_lshl_add_u64 v[68:69], v[68:69], 0, s[44:45]
	v_mov_b64_e32 v[64:65], 0
	v_mov_b64_e32 v[66:67], 0
	v_add_u32_e32 v70, 32, v70
	v_cmp_le_i32_e32 vcc, s15, v70
	v_cmp_gt_i32_e64 s[0:1], s16, v70
	s_and_b64 s[18:19], vcc, s[0:1]
	v_cmp_gt_u32_e64 s[0:1], 48, v154
	s_and_b64 s[18:19], s[18:19], s[0:1]
	s_and_saveexec_b64 s[0:1], s[18:19]
	s_cbranch_execz .Lrgl_p2_8
	global_load_dwordx4 v[64:67], v[68:69], off
.Lrgl_p2_8:
	s_or_b64 exec, exec, s[0:1]
	s_waitcnt vmcnt(0)
	ds_write_b128 v71, v[220:223]
	ds_write_b128 v71, v[224:227] offset:8704
	ds_write_b128 v71, v[228:231] offset:17408
	ds_write_b128 v71, v[232:235] offset:26112
	ds_write_b128 v71, v[236:239] offset:34816
	ds_write_b128 v71, v[244:247] offset:43520
	ds_write_b128 v71, v[248:251] offset:52224
	ds_write_b128 v71, v[252:255] offset:60928
	v_add_u32_e32 v71, 0x11000, v71
	v_cmp_gt_u32_e32 vcc, 48, v154
	s_and_saveexec_b64 s[0:1], vcc
	ds_write_b128 v71, v[64:67]
	s_or_b64 exec, exec, s[0:1]
.LBB0_1665:
	v_add_u32_e32 v64, s76, v155
	s_cmp_eq_u32 s62, s14
	v_ashrrev_i32_e32 v65, 31, v64
	s_cbranch_scc1 .LBB0_1672
	s_ashr_i32 s63, s62, 31
	s_lshl_b64 s[0:1], s[62:63], 15
	v_lshl_add_u64 v[48:49], v[164:165], 0, s[0:1]
	v_add_co_u32_e32 v20, vcc, 0xa0000, v48
	v_lshlrev_b64 v[56:57], 2, v[64:65]
	v_lshl_add_u64 v[28:29], v[48:49], 0, s[46:47]
	v_addc_co_u32_e32 v21, vcc, 0, v49, vcc
	v_lshl_add_u64 v[32:33], s[34:35], 0, v[56:57]
	global_load_dwordx4 v[0:3], v[48:49], off
	global_load_dwordx4 v[4:7], v[48:49], off offset:64
	global_load_dwordx4 v[8:11], v[48:49], off offset:128
	global_load_dwordx4 v[12:15], v[48:49], off offset:192
	global_load_dwordx4 v[16:19], v[28:29], off offset:64
	global_load_dwordx4 v[24:27], v[28:29], off offset:128
	s_nop 0
	global_load_dwordx4 v[20:23], v[20:21], off
	s_nop 0
	global_load_dwordx4 v[28:31], v[28:29], off offset:192
	v_lshl_add_u64 v[44:45], v[48:49], 0, s[48:49]
	global_load_dword v78, v[32:33], off
	v_add_co_u32_e32 v32, vcc, s84, v32
	v_lshl_add_u64 v[60:61], v[48:49], 0, s[50:51]
	s_nop 0
	v_addc_co_u32_e32 v33, vcc, 0, v33, vcc
	global_load_dword v79, v[32:33], off offset:1024
	v_add_co_u32_e32 v36, vcc, 0x50000, v48
	v_lshl_add_u64 v[62:63], s[28:29], 0, v[56:57]
	s_nop 0
	v_addc_co_u32_e32 v37, vcc, 0, v49, vcc
	v_add_co_u32_e32 v58, vcc, 0xf0000, v48
	global_load_dwordx4 v[32:35], v[44:45], off offset:64
	global_load_dwordx4 v[40:43], v[44:45], off offset:128
	s_nop 0
	global_load_dwordx4 v[36:39], v[36:37], off
	s_nop 0
	global_load_dwordx4 v[44:47], v[44:45], off offset:192
	v_addc_co_u32_e32 v59, vcc, 0, v49, vcc
	global_load_dwordx4 v[48:51], v[60:61], off offset:64
	global_load_dwordx4 v[52:55], v[60:61], off offset:128
	global_load_dword v68, v[62:63], off
	v_add_co_u32_e32 v62, vcc, s84, v62
	v_lshl_add_u64 v[56:57], s[30:31], 0, v[56:57]
	s_nop 0
	v_addc_co_u32_e32 v63, vcc, 0, v63, vcc
	global_load_dword v66, v[56:57], off
	v_add_co_u32_e32 v56, vcc, s84, v56
	global_load_dword v69, v[62:63], off offset:1024
	s_nop 0
	v_addc_co_u32_e32 v57, vcc, 0, v57, vcc
	global_load_dword v67, v[56:57], off offset:1024
	s_nop 0
	global_load_dwordx4 v[56:59], v[58:59], off
	s_nop 0
	global_load_dwordx4 v[60:63], v[60:61], off offset:192
	s_waitcnt vmcnt(13)
	v_mul_f32_e64 v70, |v78|, s52
	v_fma_f32 v71, |v78|, s52, -v70
	v_rndne_f32_e32 v72, v70
	v_fma_f32 v71, |v78|, s57, v71
	v_sub_f32_e32 v70, v70, v72
	v_add_f32_e32 v70, v70, v71
	s_waitcnt vmcnt(12)
	v_mul_f32_e64 v73, |v79|, s52
	v_fma_f32 v74, |v79|, s52, -v73
	v_rndne_f32_e32 v75, v73
	v_cvt_i32_f32_e32 v72, v72
	v_fma_f32 v71, |v79|, s57, v74
	v_sub_f32_e32 v73, v73, v75
	v_exp_f32_e32 v70, v70
	v_add_f32_e32 v71, v73, v71
	v_cvt_i32_f32_e32 v74, v75
	v_exp_f32_e32 v71, v71
	v_ldexp_f32 v70, v70, v72
	v_cmp_ngt_f32_e64 vcc, |v78|, s59
	v_ldexp_f32 v71, v71, v74
	s_nop 0
	v_cndmask_b32_e32 v70, 0, v70, vcc
	v_cmp_nlt_f32_e64 vcc, |v78|, s61
	s_nop 1
	v_cndmask_b32_e32 v76, v195, v70, vcc
	v_cmp_ngt_f32_e64 vcc, |v79|, s59
	v_add_f32_e32 v80, 1.0, v76
	v_cmp_lt_f32_e64 s[16:17], |v76|, s86
	v_cndmask_b32_e32 v70, 0, v71, vcc
	v_cmp_nlt_f32_e64 vcc, |v79|, s61
	s_nop 1
	v_cndmask_b32_e32 v77, v195, v70, vcc
	v_add_f32_e32 v81, 1.0, v77
	v_frexp_mant_f32_e32 v70, v80
	v_frexp_mant_f32_e32 v71, v81
	v_cmp_neq_f32_e32 vcc, s65, v76
	v_cmp_neq_f32_e64 s[12:13], s65, v77
	v_cmp_lt_f32_e64 s[14:15], |v77|, s86
	v_cmp_gt_f32_e64 s[0:1], s85, v70
	v_cmp_gt_f32_e64 s[18:19], s85, v71
	s_and_saveexec_b64 s[78:79], s[2:3]
	s_cbranch_execz .LBB0_1671
	v_or_b32_e32 v70, s76, v187
	v_ashrrev_i32_e32 v71, 31, v70
	v_lshl_add_u64 v[72:73], v[70:71], 2, s[26:27]
	s_mov_b64 s[80:81], 0
	v_mov_b32_e32 v71, v191
	v_mov_b32_e32 v82, v190
	v_mov_b32_e32 v83, v154
	s_branch .LBB0_1669
